# strategy 4 mirrored: static s_setprio 1 for waves 0-3, per-segment flips in the K-loops deleted
# speedup vs baseline: 1.0031x; 1.0031x over previous
; #define LAS __attribute__((address_space(3)))
; __device__ __forceinline__ void xcd_barrier_complete(unsigned* bar, unsigned x, unsigned& nloc, unsigned& nx) {
;     const unsigned G = gridDim.x * gridDim.y * gridDim.z;
;     unsigned sum, cnt, mine, sp = 0u;
;     for (;;) {
;         sum = 0u; cnt = 0u; mine = 0u;
; #pragma unroll
;         for (unsigned j = 0; j < 16; ++j) { const unsigned c = xb_ld(&bar[XB_XCNT(j)]); sum += c; cnt += (c > 0u) ? 1u : 0u; mine = (j == x) ? c : mine; }
;         if (sum == G) break;
;         __builtin_amdgcn_s_sleep(1);
;         if ((++sp & 255u) == 0u) { if (xb_ld(&bar[XB_TMO])) break; if (sp > XB_SPIN_CAP) { atomicAdd(&bar[XB_TMO], 1u); break; } }
;     }
;     nloc = mine > 0u ? mine : 1u; nx = cnt > 0u ? cnt : 1u;
; }
; __device__ __forceinline__ void xcd_barrier(const XcdBarrier& b, int wave) {
;     asm volatile("s_waitcnt vmcnt(0)" ::: "memory");
;     __syncthreads();
;     if (xb_leader(wave)) {
;         unsigned* bar = b.bar;
;         __builtin_amdgcn_s_waitcnt(0);
;         unsigned nloc = b.st[0], nx = b.st[1];
;         if (nloc == 0u) { xcd_barrier_complete(bar, b.x, nloc, nx); b.st[0] = nloc; b.st[1] = nx; }
;         const unsigned old = xb_add(&bar[XB_XSUB(b.x)], 1u);
;         const unsigned gen = old / nloc;
;         if (old + 1u == (gen + 1u) * nloc) {
;             __builtin_amdgcn_fence(__ATOMIC_RELEASE, "agent");
;             asm volatile("s_waitcnt vmcnt(0)" ::: "memory");
;             const unsigned og = xb_add(&bar[XB_TOP], 1u);
;             const unsigned tg = og / nx;
;             if (og + 1u == (tg + 1u) * nx) xb_add(&bar[XB_TOPGEN], 1u);
;             else XB_SPIN(xb_ld(&bar[XB_TOPGEN]) == tg, bar);
;             __builtin_amdgcn_fence(__ATOMIC_ACQUIRE, "agent");
;             xb_add(&bar[XB_XGEN(b.x)], 1u);
;             asm volatile("s_waitcnt vmcnt(0)" ::: "memory");
;         } else {
;             XB_SPIN(xb_ld(&bar[XB_XGEN(b.x)]) == gen, bar);
;             __builtin_amdgcn_fence(__ATOMIC_ACQUIRE, "agent");
;             asm volatile("s_waitcnt vmcnt(0)" ::: "memory");
;         }
;     }
;     __syncthreads();
; }
; __global__ void __launch_bounds__(NTHREADS, 2) mega_fwd(Args args) {
;     ...
;     const XcdBarrier xbar = xcd_barrier_post((unsigned*)(args.ws + WS_BAR), (volatile LAS unsigned*)(lds + XB_ST_OFF), wave);
; #pragma unroll 1
;     for (int l = 0; l < DEPTH; ++l) {
.LBB0_201:
	s_or_b64 exec, exec, s[4:5]
	s_load_dwordx4 s[12:15], s[0:1], 0x88
	s_load_dword s5, s[0:1], 0x98
	v_add_u32_e32 v0, 64, v74
	v_cmp_lt_i32_e32 vcc, v73, v0
	v_mov_b32_e32 v220, 0x358637bd
	s_waitcnt lgkmcnt(0)
	s_mul_i32 s4, s15, s14
	s_mul_i32 s36, s4, s5
	s_add_u32 s4, s12, 0x80200
	s_addc_u32 s5, s13, 0
	s_add_u32 s58, s12, 0x80400
	v_writelane_b32 v254, s4, 4
	s_addc_u32 s59, s13, 0
	v_cndmask_b32_e32 v1, v211, v73, vcc
	v_writelane_b32 v254, s5, 5
	s_add_u32 s4, s12, 0x80500
	s_addc_u32 s5, s13, 0
	v_writelane_b32 v254, s4, 6
	v_cmp_lt_i32_e32 vcc, v72, v0
	v_lshlrev_b32_e32 v218, 2, v1
	v_writelane_b32 v254, s5, 7
	s_add_u32 s4, s12, 0x80600
	s_addc_u32 s5, s13, 0
	v_writelane_b32 v254, s4, 8
	v_cndmask_b32_e32 v0, v211, v72, vcc
	v_lshlrev_b32_e32 v219, 2, v0
	v_writelane_b32 v254, s5, 9
	s_add_u32 s4, s12, 0x80700
	s_addc_u32 s5, s13, 0
	v_writelane_b32 v254, s4, 10
	s_movk_i32 s33, 0x2000
	v_mov_b32_e32 v97, 0
	v_writelane_b32 v254, s5, 11
	s_add_u32 s4, s12, 0x80800
	s_addc_u32 s5, s13, 0
	v_writelane_b32 v254, s4, 12
	s_mov_b32 s62, 0xffff0000
	s_movk_i32 s63, 0x2c00
	v_writelane_b32 v254, s5, 13
	s_add_u32 s4, s12, 0x80900
	s_addc_u32 s5, s13, 0
	v_writelane_b32 v254, s4, 14
	v_mov_b32_e32 v221, 1
	v_mov_b64_e32 v[194:195], 0x57f
	v_writelane_b32 v254, s5, 15
	s_add_u32 s4, s12, 0x80a00
	s_addc_u32 s5, s13, 0
	v_writelane_b32 v254, s4, 16
	v_mov_b64_e32 v[252:253], 0x580
	v_mov_b64_e32 v[200:201], 0xff
	v_writelane_b32 v254, s5, 17
	s_add_u32 s4, s12, 0x80b00
	s_addc_u32 s5, s13, 0
	v_writelane_b32 v254, s4, 18
	v_mov_b32_e32 v222, 0xff800000
	v_mov_b32_e32 v223, 0x42800000
	v_writelane_b32 v254, s5, 19
	s_add_u32 s4, s12, 0x80c00
	s_addc_u32 s5, s13, 0
	v_writelane_b32 v254, s4, 20
	v_not_b32_e32 v224, 63
	v_mov_b32_e32 v225, 0x1fff
	v_writelane_b32 v254, s5, 21
	s_add_u32 s4, s12, 0x80d00
	s_addc_u32 s5, s13, 0
	v_writelane_b32 v254, s4, 22
	s_mov_b64 s[34:35], 0
	s_mov_b64 s[22:23], 0x80
	v_writelane_b32 v254, s5, 23
	s_add_u32 s4, s12, 0x80e00
	s_addc_u32 s5, s13, 0
	v_writelane_b32 v254, s4, 24
	s_mov_b64 s[24:25], 0x100
	s_mov_b32 s56, s77
	v_writelane_b32 v254, s5, 25
	s_add_u32 s4, s12, 0x80f00
	s_addc_u32 s5, s13, 0
	v_writelane_b32 v254, s4, 26
	s_nop 1
	v_writelane_b32 v254, s5, 27
	s_add_u32 s4, s12, 0x81000
	s_addc_u32 s5, s13, 0
	v_writelane_b32 v254, s4, 28
	s_nop 1
	v_writelane_b32 v254, s5, 29
	s_add_u32 s4, s12, 0x81100
	s_addc_u32 s5, s13, 0
	v_writelane_b32 v254, s4, 30
	s_nop 1
	v_writelane_b32 v254, s5, 31
	s_add_u32 s4, s12, 0x81200
	s_addc_u32 s5, s13, 0
	v_writelane_b32 v254, s4, 32
	s_nop 1
	v_writelane_b32 v254, s5, 33
	s_add_u32 s4, s12, 0x81300
	s_addc_u32 s5, s13, 0
	v_writelane_b32 v254, s4, 34
	s_cmp_eq_u32 s8, 15
	s_nop 0
	v_writelane_b32 v254, s5, 35
	s_cselect_b64 s[4:5], -1, 0
	v_writelane_b32 v254, s4, 36
	s_cmp_eq_u32 s8, 14
	s_nop 0
	v_writelane_b32 v254, s5, 37
	s_cselect_b64 s[4:5], -1, 0
	v_writelane_b32 v254, s4, 38
	s_cmp_eq_u32 s8, 13
	s_nop 0
	v_writelane_b32 v254, s5, 39
	s_cselect_b64 s[4:5], -1, 0
	v_writelane_b32 v254, s4, 40
	s_cmp_eq_u32 s8, 12
	s_nop 0
	v_writelane_b32 v254, s5, 41
	s_cselect_b64 s[4:5], -1, 0
	v_writelane_b32 v254, s4, 42
	s_cmp_eq_u32 s8, 11
	s_nop 0
	v_writelane_b32 v254, s5, 43
	s_cselect_b64 s[4:5], -1, 0
	v_writelane_b32 v254, s4, 44
	s_cmp_eq_u32 s8, 10
	s_nop 0
	v_writelane_b32 v254, s5, 45
	s_cselect_b64 s[4:5], -1, 0
	v_writelane_b32 v254, s4, 46
	s_cmp_eq_u32 s8, 9
	s_nop 0
	v_writelane_b32 v254, s5, 47
	s_cselect_b64 s[4:5], -1, 0
	v_writelane_b32 v254, s4, 48
	s_cmp_eq_u32 s8, 8
	s_nop 0
	v_writelane_b32 v254, s5, 49
	s_cselect_b64 s[4:5], -1, 0
	v_writelane_b32 v254, s4, 50
	s_cmp_eq_u32 s8, 7
	s_nop 0
	v_writelane_b32 v254, s5, 51
	s_cselect_b64 s[4:5], -1, 0
	v_writelane_b32 v254, s4, 52
	s_cmp_eq_u32 s8, 6
	s_nop 0
	v_writelane_b32 v254, s5, 53
	s_cselect_b64 s[4:5], -1, 0
	v_writelane_b32 v254, s4, 54
	s_cmp_eq_u32 s8, 5
	s_nop 0
	v_writelane_b32 v254, s5, 55
	s_cselect_b64 s[4:5], -1, 0
	v_writelane_b32 v254, s4, 56
	s_cmp_eq_u32 s8, 4
	s_nop 0
	v_writelane_b32 v254, s5, 57
	s_cselect_b64 s[4:5], -1, 0
	v_writelane_b32 v254, s4, 58
	s_cmp_eq_u32 s8, 3
	s_nop 0
	v_writelane_b32 v254, s5, 59
	s_cselect_b64 s[4:5], -1, 0
	v_writelane_b32 v254, s4, 60
	s_cmp_eq_u32 s8, 2
	s_nop 0
	v_writelane_b32 v254, s5, 61
	s_cselect_b64 s[4:5], -1, 0
	v_writelane_b32 v254, s4, 62
	s_cmp_eq_u32 s8, 1
	s_nop 0
	v_writelane_b32 v254, s5, 63
	s_cselect_b64 s[4:5], -1, 0
	v_writelane_b32 v255, s4, 0
	s_cmp_eq_u32 s8, 0
	s_nop 0
	v_writelane_b32 v255, s5, 1
	s_cselect_b64 s[4:5], -1, 0
	v_writelane_b32 v255, s4, 2
	s_nop 1
	v_writelane_b32 v255, s5, 3
	s_lshl_b32 s4, s9, 2
	s_add_u32 s2, s2, s4
	s_addc_u32 s3, s3, 0
	s_add_u32 s4, s2, 0x1400
	s_addc_u32 s5, s3, 0
	v_writelane_b32 v255, s4, 4
	s_add_u32 s2, s2, 0x2400
	s_addc_u32 s3, s3, 0
	v_writelane_b32 v255, s5, 5
	v_writelane_b32 v255, s2, 6
	s_load_dwordx2 s[20:21], s[0:1], 0x80
	s_load_dwordx4 s[8:11], s[0:1], 0x38
	v_writelane_b32 v255, s0, 62
	v_writelane_b32 v255, s1, 63
	v_writelane_b32 v255, s3, 7
	s_add_u32 s2, s12, 0x83400
	s_addc_u32 s3, s13, 0
	v_writelane_b32 v255, s2, 8
	s_movk_i32 s4, 0x81
	s_movk_i32 s5, 0x7fff
	v_writelane_b32 v255, s3, 9
	s_add_u32 s2, s12, 0x83500
	s_addc_u32 s3, s13, 0
	v_writelane_b32 v255, s2, 10
	s_nop 1
	v_writelane_b32 v255, s3, 11
	s_add_i32 s2, 0, 0x26440
	v_writelane_b32 v255, s2, 12
	s_add_i32 s2, 0, 0x26444
	v_writelane_b32 v255, s2, 13
	s_waitcnt lgkmcnt(0)
	v_writelane_b32 v255, s8, 14
	s_mov_b64 s[2:3], -1
	s_nop 0
	v_writelane_b32 v255, s9, 15
	v_writelane_b32 v255, s10, 16
	v_writelane_b32 v255, s11, 17
	v_writelane_b32 v255, s72, 18
	v_writelane_b32 v255, s73, 19
	v_writelane_b32 v255, s78, 20
	s_nop 1
	v_writelane_b32 v255, s79, 21
	v_writelane_b32 v255, s36, 22
	v_writelane_b32 v255, s58, 23
	s_nop 1
	v_writelane_b32 v255, s59, 24
	s_cmp_lt_u32 s73, 4
	s_cbranch_scc0 .Lprio_done
	s_setprio 1
